# attention: next-tile K/V global loads issued in the post-QK MFMA wait shadow (replaces s_nop 10); MLP-up epilogue without redundant canonicalizing max; no grid barrier between the independent L1_G and
# speedup vs baseline: 1.0249x; 1.0016x over previous
.LBB0_357:
	s_and_b32 s12, s21, 1
	s_mul_i32 s13, s12, 0x2400
	v_add_u32_e32 v0, s13, v128
	ds_read_b128 v[48:51], v0
	ds_read_b128 v[52:55], v0 offset:32
	s_waitcnt lgkmcnt(1)
	v_mfma_f32_32x32x16_bf16 v[64:79], v[48:51], v[92:95], 0
	ds_read_b128 v[48:51], v0 offset:64
	ds_read_b128 v[132:135], v0 offset:96
	s_waitcnt lgkmcnt(2)
	v_mfma_f32_32x32x16_bf16 v[64:79], v[52:55], v[88:91], v[64:79]
	s_waitcnt lgkmcnt(1)
	v_mfma_f32_32x32x16_bf16 v[64:79], v[48:51], v[84:87], v[64:79]
	ds_read_b128 v[48:51], v0 offset:4608
	ds_read_b128 v[136:139], v0 offset:4640
	s_waitcnt lgkmcnt(1)
	v_mfma_f32_32x32x16_bf16 v[48:63], v[48:51], v[92:95], 0
	s_waitcnt lgkmcnt(0)
	v_mfma_f32_32x32x16_bf16 v[48:63], v[136:139], v[88:91], v[48:63]
	ds_read_b128 v[136:139], v0 offset:4672
	ds_read_b128 v[140:143], v0 offset:4704
	s_waitcnt lgkmcnt(1)
	v_mfma_f32_32x32x16_bf16 v[48:63], v[136:139], v[84:87], v[48:63]
	s_waitcnt lgkmcnt(0)
	v_mfma_f32_32x32x16_bf16 v[48:63], v[140:143], v[80:83], v[48:63]
	v_mfma_f32_32x32x16_bf16 v[64:79], v[132:135], v[80:83], v[64:79]
	v_lshl_add_u64 v[2:3], v[124:125], 0, s[10:11]
	v_add_co_u32_e32 v4, vcc, 0xaa08000, v2
	v_lshl_add_u64 v[14:15], v[122:123], 0, s[10:11]
	s_nop 0
	v_addc_co_u32_e32 v5, vcc, 0, v3, vcc
	v_add_co_u32_e32 v2, vcc, 0xaa0c000, v2
	s_nop 0
	v_addc_co_u32_e32 v3, vcc, 0, v3, vcc
	global_load_dwordx4 v[10:13], v[4:5], off
	global_load_dwordx4 v[96:99], v[2:3], off
	s_nop 0
	global_load_dwordx4 v[2:5], v[14:15], off offset:-512
	global_load_dwordx4 v[6:9], v[14:15], off
	v_max_f32_e32 v0, v48, v48
	v_max_f32_e32 v14, v64, v64
	v_max_f32_e32 v0, v14, v0
	v_max3_f32 v0, v0, v65, v49
	v_max3_f32 v0, v0, v66, v50
	v_max3_f32 v0, v0, v67, v51
	v_max3_f32 v0, v0, v68, v52
	v_max3_f32 v0, v0, v69, v53
	v_max3_f32 v0, v0, v70, v54
	v_max3_f32 v0, v0, v71, v55
	v_max3_f32 v0, v0, v72, v56
	v_max3_f32 v0, v0, v73, v57
	v_max3_f32 v0, v0, v74, v58
	v_max3_f32 v0, v0, v75, v59
	v_max3_f32 v0, v0, v76, v60
	v_max3_f32 v0, v0, v77, v61
	v_max3_f32 v0, v0, v78, v62
	v_max3_f32 v0, v0, v79, v63
	ds_bpermute_b32 v14, v129, v0
	s_waitcnt lgkmcnt(0)
	v_max_f32_e32 v14, v14, v14
	v_max_f32_e32 v0, v0, v14
	v_mul_f32_e32 v0, 0x3e38aa3b, v0
	v_add_f32_e32 v14, 0x41000000, v120
	v_cmp_gt_f32_e32 vcc, v0, v14
	s_cbranch_vccz .LBB0_356
	v_max_f32_e32 v0, v0, v0
	v_max_f32_e32 v14, v120, v120
	v_max_f32_e32 v14, v14, v0
	v_sub_f32_e32 v0, v120, v14
	v_exp_f32_e32 v0, v0
	v_mov_b32_e32 v120, v14
	v_pk_mul_f32 v[46:47], v[46:47], v[0:1] op_sel_hi:[1,0]
	v_pk_mul_f32 v[44:45], v[44:45], v[0:1] op_sel_hi:[1,0]
	v_pk_mul_f32 v[42:43], v[42:43], v[0:1] op_sel_hi:[1,0]
	v_pk_mul_f32 v[40:41], v[40:41], v[0:1] op_sel_hi:[1,0]
	v_pk_mul_f32 v[38:39], v[38:39], v[0:1] op_sel_hi:[1,0]
	v_pk_mul_f32 v[36:37], v[36:37], v[0:1] op_sel_hi:[1,0]
	v_pk_mul_f32 v[34:35], v[34:35], v[0:1] op_sel_hi:[1,0]
	v_pk_mul_f32 v[32:33], v[32:33], v[0:1] op_sel_hi:[1,0]
	v_pk_mul_f32 v[30:31], v[30:31], v[0:1] op_sel_hi:[1,0]
	v_pk_mul_f32 v[28:29], v[28:29], v[0:1] op_sel_hi:[1,0]
	v_pk_mul_f32 v[26:27], v[26:27], v[0:1] op_sel_hi:[1,0]
	v_pk_mul_f32 v[24:25], v[24:25], v[0:1] op_sel_hi:[1,0]
	v_pk_mul_f32 v[22:23], v[22:23], v[0:1] op_sel_hi:[1,0]
	v_pk_mul_f32 v[20:21], v[20:21], v[0:1] op_sel_hi:[1,0]
	v_pk_mul_f32 v[18:19], v[18:19], v[0:1] op_sel_hi:[1,0]
	v_pk_mul_f32 v[16:17], v[16:17], v[0:1] op_sel_hi:[1,0]
	v_mul_f32_e32 v115, v115, v0
	s_branch .LBB0_356

.LBB0_607:
	v_add_u32_e32 v16, s10, v129
	ds_read_b128 v[4:7], v16
	ds_read_b128 v[8:11], v16 offset:16
	ds_read_b128 v[12:15], v16 offset:32
	ds_read_b128 v[16:19], v16 offset:48
	v_ashrrev_i32_e32 v3, 31, v2
	v_lshlrev_b64 v[20:21], 13, v[2:3]
	s_waitcnt lgkmcnt(3)
	s_waitcnt lgkmcnt(2)
	s_waitcnt lgkmcnt(1)
	s_waitcnt lgkmcnt(0)
	v_max_f32_e32 v4, 0, v4
	v_max_f32_e32 v5, 0, v5
	v_max_f32_e32 v6, 0, v6
	v_max_f32_e32 v7, 0, v7
	v_max_f32_e32 v8, 0, v8
	v_max_f32_e32 v9, 0, v9
	v_max_f32_e32 v10, 0, v10
	v_max_f32_e32 v11, 0, v11
	s_addk_i32 s10, 0x4200
	v_max_f32_e32 v12, 0, v12
	v_max_f32_e32 v13, 0, v13
	v_max_f32_e32 v14, 0, v14
	v_max_f32_e32 v15, 0, v15
	v_max_f32_e32 v16, 0, v16
	v_max_f32_e32 v17, 0, v17
	v_max_f32_e32 v18, 0, v18
	v_max_f32_e32 v19, 0, v19
	v_pk_mul_f32 v[4:5], v[4:5], v[4:5]
	v_pk_mul_f32 v[6:7], v[6:7], v[6:7]
	v_pk_mul_f32 v[8:9], v[8:9], v[8:9]
	v_pk_mul_f32 v[10:11], v[10:11], v[10:11]
	v_add_u32_e32 v2, 32, v2
	s_cmp_lg_u32 s10, 0x10800
	v_lshl_add_u64 v[20:21], v[0:1], 0, v[20:21]
	v_pk_mul_f32 v[12:13], v[12:13], v[12:13]
	v_pk_mul_f32 v[14:15], v[14:15], v[14:15]
	v_pk_mul_f32 v[16:17], v[16:17], v[16:17]
	v_pk_mul_f32 v[18:19], v[18:19], v[18:19]
	v_cvt_pk_bf16_f32 v4, v4, v5
	v_cvt_pk_bf16_f32 v5, v6, v7
	v_cvt_pk_bf16_f32 v6, v8, v9
	v_cvt_pk_bf16_f32 v7, v10, v11
	v_cvt_pk_bf16_f32 v8, v12, v13
	v_cvt_pk_bf16_f32 v9, v14, v15
	v_cvt_pk_bf16_f32 v10, v16, v17
	v_cvt_pk_bf16_f32 v11, v18, v19
	global_store_dwordx4 v[20:21], v[4:7], off
	global_store_dwordx4 v[20:21], v[8:11], off offset:16
	s_cbranch_scc1 .LBB0_607
	s_add_i32 s14, s14, s56
	v_add_u32_e32 v122, s12, v122
	v_add_u32_e32 v123, s12, v123
	v_add_u32_e32 v125, s12, v125
	s_cmpk_gt_i32 s14, 0x11ff
	v_add_u32_e32 v64, s12, v64
	s_barrier
	s_cbranch_scc0 .LBB0_604

.LBB0_618:
	v_add_u32_e32 v16, s6, v129
	ds_read_b128 v[4:7], v16
	ds_read_b128 v[8:11], v16 offset:16
	ds_read_b128 v[12:15], v16 offset:32
	ds_read_b128 v[16:19], v16 offset:48
	v_ashrrev_i32_e32 v3, 31, v2
	v_lshlrev_b64 v[20:21], 13, v[2:3]
	s_waitcnt lgkmcnt(3)
	s_waitcnt lgkmcnt(2)
	s_waitcnt lgkmcnt(1)
	s_waitcnt lgkmcnt(0)
	v_max_f32_e32 v4, 0, v4
	v_max_f32_e32 v5, 0, v5
	v_max_f32_e32 v6, 0, v6
	v_max_f32_e32 v7, 0, v7
	v_max_f32_e32 v8, 0, v8
	v_max_f32_e32 v9, 0, v9
	v_max_f32_e32 v10, 0, v10
	v_max_f32_e32 v11, 0, v11
	s_addk_i32 s6, 0x4200
	v_max_f32_e32 v12, 0, v12
	v_max_f32_e32 v13, 0, v13
	v_max_f32_e32 v14, 0, v14
	v_max_f32_e32 v15, 0, v15
	v_max_f32_e32 v16, 0, v16
	v_max_f32_e32 v17, 0, v17
	v_max_f32_e32 v18, 0, v18
	v_max_f32_e32 v19, 0, v19
	v_pk_mul_f32 v[4:5], v[4:5], v[4:5]
	v_pk_mul_f32 v[6:7], v[6:7], v[6:7]
	v_pk_mul_f32 v[8:9], v[8:9], v[8:9]
	v_pk_mul_f32 v[10:11], v[10:11], v[10:11]
	v_add_u32_e32 v2, 32, v2
	s_cmp_lg_u32 s6, 0x10800
	v_lshl_add_u64 v[20:21], v[0:1], 0, v[20:21]
	v_pk_mul_f32 v[12:13], v[12:13], v[12:13]
	v_pk_mul_f32 v[14:15], v[14:15], v[14:15]
	v_pk_mul_f32 v[16:17], v[16:17], v[16:17]
	v_pk_mul_f32 v[18:19], v[18:19], v[18:19]
	v_cvt_pk_bf16_f32 v4, v4, v5
	v_cvt_pk_bf16_f32 v5, v6, v7
	v_cvt_pk_bf16_f32 v6, v8, v9
	v_cvt_pk_bf16_f32 v7, v10, v11
	v_cvt_pk_bf16_f32 v8, v12, v13
	v_cvt_pk_bf16_f32 v9, v14, v15
	v_cvt_pk_bf16_f32 v10, v16, v17
	v_cvt_pk_bf16_f32 v11, v18, v19
	global_store_dwordx4 v[20:21], v[4:7], off
	global_store_dwordx4 v[20:21], v[8:11], off offset:16
	s_cbranch_scc1 .LBB0_618
	s_add_i32 s10, s10, s11
	s_cmpk_gt_i32 s10, 0x23f
	s_barrier
	s_cbranch_scc0 .LBB0_613

.LBB0_1539:
	s_load_dword s6, s[0:1], 0x1fc
	s_waitcnt lgkmcnt(0)
	s_cmp_lt_i32 s6, 13
	s_branch .LBB0_1593
	s_waitcnt vmcnt(0)
	s_barrier
	s_and_saveexec_b64 s[6:7], s[46:47]
	s_cbranch_execz .LBB0_1592
	v_mov_b32_e32 v0, 0
	s_waitcnt vmcnt(0) expcnt(0) lgkmcnt(0)
	ds_read_b32 v2, v0
	ds_read_b32 v1, v0 offset:4
	s_waitcnt lgkmcnt(1)
	v_cmp_ne_u32_e32 vcc, 0, v2
	s_cbranch_vccnz .LBB0_1556
	s_add_u32 s8, s52, 0x14e28200
	s_addc_u32 s9, s53, 0
	s_add_u32 s10, s52, 0x14e28400
	s_addc_u32 s11, s53, 0
	s_add_u32 s12, s52, 0x14e28500
	s_addc_u32 s13, s53, 0
	s_add_u32 s14, s52, 0x14e28600
	s_addc_u32 s15, s53, 0
	s_add_u32 s16, s52, 0x14e28700
	s_addc_u32 s17, s53, 0
	s_add_u32 s18, s52, 0x14e28800
	s_addc_u32 s19, s53, 0
	s_add_u32 s20, s52, 0x14e28900
	s_addc_u32 s21, s53, 0
	s_add_u32 s22, s52, 0x14e28a00
	s_addc_u32 s23, s53, 0
	s_add_u32 s24, s52, 0x14e28b00
	s_addc_u32 s25, s53, 0
	s_add_u32 s26, s52, 0x14e28c00
	s_addc_u32 s27, s53, 0
	s_add_u32 s28, s52, 0x14e28d00
	s_addc_u32 s29, s53, 0
	s_add_u32 s30, s52, 0x14e28e00
	s_addc_u32 s31, s53, 0
	s_add_u32 s34, s52, 0x14e28f00
	s_addc_u32 s35, s53, 0
	s_add_u32 s36, s52, 0x14e29000
	s_addc_u32 s37, s53, 0
	s_add_u32 s38, s52, 0x14e29100
	s_addc_u32 s39, s53, 0
	s_add_u32 s40, s52, 0x14e29200
	s_addc_u32 s41, s53, 0
	s_mul_i32 s58, s57, s3
	s_add_u32 s42, s52, 0x14e29300
	s_mul_i32 s58, s58, s56
	s_addc_u32 s43, s53, 0
	s_mov_b32 s59, 1
	s_branch .LBB0_1544

.LBB0_2000:
	v_add_u32_e32 v16, s12, v129
	ds_read_b128 v[4:7], v16
	ds_read_b128 v[8:11], v16 offset:16
	ds_read_b128 v[12:15], v16 offset:32
	ds_read_b128 v[16:19], v16 offset:48
	v_ashrrev_i32_e32 v3, 31, v2
	v_lshlrev_b64 v[20:21], 13, v[2:3]
	s_waitcnt lgkmcnt(3)
	s_waitcnt lgkmcnt(2)
	s_waitcnt lgkmcnt(1)
	s_waitcnt lgkmcnt(0)
	v_max_f32_e32 v4, 0, v4
	v_max_f32_e32 v5, 0, v5
	v_max_f32_e32 v6, 0, v6
	v_max_f32_e32 v7, 0, v7
	v_max_f32_e32 v8, 0, v8
	v_max_f32_e32 v9, 0, v9
	v_max_f32_e32 v10, 0, v10
	v_max_f32_e32 v11, 0, v11
	s_addk_i32 s12, 0x4200
	v_max_f32_e32 v12, 0, v12
	v_max_f32_e32 v13, 0, v13
	v_max_f32_e32 v14, 0, v14
	v_max_f32_e32 v15, 0, v15
	v_max_f32_e32 v16, 0, v16
	v_max_f32_e32 v17, 0, v17
	v_max_f32_e32 v18, 0, v18
	v_max_f32_e32 v19, 0, v19
	v_pk_mul_f32 v[4:5], v[4:5], v[4:5]
	v_pk_mul_f32 v[6:7], v[6:7], v[6:7]
	v_pk_mul_f32 v[8:9], v[8:9], v[8:9]
	v_pk_mul_f32 v[10:11], v[10:11], v[10:11]
	v_add_u32_e32 v2, 32, v2
	s_cmp_lg_u32 s12, 0x10800
	v_lshl_add_u64 v[20:21], v[0:1], 0, v[20:21]
	v_pk_mul_f32 v[12:13], v[12:13], v[12:13]
	v_pk_mul_f32 v[14:15], v[14:15], v[14:15]
	v_pk_mul_f32 v[16:17], v[16:17], v[16:17]
	v_pk_mul_f32 v[18:19], v[18:19], v[18:19]
	v_cvt_pk_bf16_f32 v4, v4, v5
	v_cvt_pk_bf16_f32 v5, v6, v7
	v_cvt_pk_bf16_f32 v6, v8, v9
	v_cvt_pk_bf16_f32 v7, v10, v11
	v_cvt_pk_bf16_f32 v8, v12, v13
	v_cvt_pk_bf16_f32 v9, v14, v15
	v_cvt_pk_bf16_f32 v10, v16, v17
	v_cvt_pk_bf16_f32 v11, v18, v19
	global_store_dwordx4 v[20:21], v[4:7], off
	global_store_dwordx4 v[20:21], v[8:11], off offset:16
	s_cbranch_scc1 .LBB0_2000
	s_add_i32 s16, s16, s56
	v_add_u32_e32 v122, s14, v122
	v_add_u32_e32 v123, s14, v123
	v_add_u32_e32 v125, s14, v125
	s_cmpk_gt_i32 s16, 0x11ff
	v_add_u32_e32 v64, s14, v64
	s_barrier
	s_cbranch_scc0 .LBB0_1997

.LBB0_2011:
	v_add_u32_e32 v16, s8, v129
	ds_read_b128 v[4:7], v16
	ds_read_b128 v[8:11], v16 offset:16
	ds_read_b128 v[12:15], v16 offset:32
	ds_read_b128 v[16:19], v16 offset:48
	v_ashrrev_i32_e32 v3, 31, v2
	v_lshlrev_b64 v[20:21], 13, v[2:3]
	s_waitcnt lgkmcnt(3)
	s_waitcnt lgkmcnt(2)
	s_waitcnt lgkmcnt(1)
	s_waitcnt lgkmcnt(0)
	v_max_f32_e32 v4, 0, v4
	v_max_f32_e32 v5, 0, v5
	v_max_f32_e32 v6, 0, v6
	v_max_f32_e32 v7, 0, v7
	v_max_f32_e32 v8, 0, v8
	v_max_f32_e32 v9, 0, v9
	v_max_f32_e32 v10, 0, v10
	v_max_f32_e32 v11, 0, v11
	s_addk_i32 s8, 0x4200
	v_max_f32_e32 v12, 0, v12
	v_max_f32_e32 v13, 0, v13
	v_max_f32_e32 v14, 0, v14
	v_max_f32_e32 v15, 0, v15
	v_max_f32_e32 v16, 0, v16
	v_max_f32_e32 v17, 0, v17
	v_max_f32_e32 v18, 0, v18
	v_max_f32_e32 v19, 0, v19
	v_pk_mul_f32 v[4:5], v[4:5], v[4:5]
	v_pk_mul_f32 v[6:7], v[6:7], v[6:7]
	v_pk_mul_f32 v[8:9], v[8:9], v[8:9]
	v_pk_mul_f32 v[10:11], v[10:11], v[10:11]
	v_add_u32_e32 v2, 32, v2
	s_cmp_lg_u32 s8, 0x10800
	v_lshl_add_u64 v[20:21], v[0:1], 0, v[20:21]
	v_pk_mul_f32 v[12:13], v[12:13], v[12:13]
	v_pk_mul_f32 v[14:15], v[14:15], v[14:15]
	v_pk_mul_f32 v[16:17], v[16:17], v[16:17]
	v_pk_mul_f32 v[18:19], v[18:19], v[18:19]
	v_cvt_pk_bf16_f32 v4, v4, v5
	v_cvt_pk_bf16_f32 v5, v6, v7
	v_cvt_pk_bf16_f32 v6, v8, v9
	v_cvt_pk_bf16_f32 v7, v10, v11
	v_cvt_pk_bf16_f32 v8, v12, v13
	v_cvt_pk_bf16_f32 v9, v14, v15
	v_cvt_pk_bf16_f32 v10, v16, v17
	v_cvt_pk_bf16_f32 v11, v18, v19
	global_store_dwordx4 v[20:21], v[4:7], off
	global_store_dwordx4 v[20:21], v[8:11], off offset:16
	s_cbranch_scc1 .LBB0_2011
	s_add_i32 s12, s12, s13
	s_cmpk_gt_i32 s12, 0x23f
	s_barrier
	s_cbranch_scc0 .LBB0_2006

.LBB0_2453:
	s_and_b32 s22, s27, 1
	s_mul_i32 s23, s22, 0x3400
	v_add_u32_e32 v162, s23, v145
	ds_read_b128 v[32:35], v162
	ds_read_b128 v[36:39], v162 offset:32
	s_waitcnt lgkmcnt(1)
	v_mfma_f32_32x32x16_bf16 v[48:63], v[32:35], v[84:87], 0
	s_waitcnt lgkmcnt(0)
	v_mfma_f32_32x32x16_bf16 v[48:63], v[36:39], v[80:83], v[48:63]
	ds_read_b128 v[32:35], v162 offset:64
	ds_read_b128 v[36:39], v162 offset:96
	s_waitcnt lgkmcnt(1)
	v_mfma_f32_32x32x16_bf16 v[48:63], v[32:35], v[76:79], v[48:63]
	ds_read_b128 v[32:35], v162 offset:128
	ds_read_b128 v[150:153], v162 offset:160
	s_waitcnt lgkmcnt(2)
	v_mfma_f32_32x32x16_bf16 v[48:63], v[36:39], v[72:75], v[48:63]
	s_waitcnt lgkmcnt(1)
	v_mfma_f32_32x32x16_bf16 v[48:63], v[32:35], v[68:71], v[48:63]
	ds_read_b128 v[32:35], v162 offset:6656
	ds_read_b128 v[154:157], v162 offset:6688
	s_waitcnt lgkmcnt(1)
	v_mfma_f32_32x32x16_bf16 v[32:47], v[32:35], v[84:87], 0
	s_waitcnt lgkmcnt(0)
	v_mfma_f32_32x32x16_bf16 v[32:47], v[154:157], v[80:83], v[32:47]
	ds_read_b128 v[154:157], v162 offset:6720
	ds_read_b128 v[158:161], v162 offset:6752
	s_waitcnt lgkmcnt(1)
	v_mfma_f32_32x32x16_bf16 v[32:47], v[154:157], v[76:79], v[32:47]
	s_waitcnt lgkmcnt(0)
	v_mfma_f32_32x32x16_bf16 v[32:47], v[158:161], v[72:75], v[32:47]
	ds_read_b128 v[154:157], v162 offset:6784
	ds_read_b128 v[158:161], v162 offset:6816
	s_waitcnt lgkmcnt(1)
	v_mfma_f32_32x32x16_bf16 v[32:47], v[154:157], v[68:71], v[32:47]
	s_waitcnt lgkmcnt(0)
	v_mfma_f32_32x32x16_bf16 v[32:47], v[158:161], v[64:67], v[32:47]
	v_mfma_f32_32x32x16_bf16 v[48:63], v[150:153], v[64:67], v[48:63]
	v_lshl_add_u64 v[184:185], s[6:7], 0, v[136:137]
	v_add_co_u32_e32 v186, vcc, 0xf220000, v184
	s_nop 0
	v_addc_co_u32_e32 v187, vcc, 0, v185, vcc
	v_add_co_u32_e32 v184, vcc, 0xf230000, v184
	s_nop 1
	v_addc_co_u32_e32 v185, vcc, 0, v185, vcc
	global_load_dwordx4 v[96:99], v[186:187], off
	global_load_dwordx4 v[100:103], v[184:185], off
	v_lshl_add_u64 v[184:185], s[6:7], 0, v[132:133]
	v_lshl_add_u64 v[186:187], s[6:7], 0, v[134:135]
	global_load_dwordx4 v[104:107], v[184:185], off
	global_load_dwordx4 v[88:91], v[186:187], off offset:-2048
	global_load_dwordx4 v[92:95], v[186:187], off
	v_max_f32_e32 v154, v32, v32
	v_max_f32_e32 v150, v48, v48
	v_max_f32_e32 v150, v150, v154
	v_max3_f32 v150, v150, v49, v33
	v_max3_f32 v150, v150, v50, v34
	v_max3_f32 v150, v150, v51, v35
	v_max3_f32 v150, v150, v52, v36
	v_max3_f32 v150, v150, v53, v37
	v_max3_f32 v150, v150, v54, v38
	v_max3_f32 v150, v150, v55, v39
	v_max3_f32 v150, v150, v56, v40
	v_max3_f32 v150, v150, v57, v41
	v_max3_f32 v150, v150, v58, v42
	v_max3_f32 v150, v150, v59, v43
	v_max3_f32 v150, v150, v60, v44
	v_max3_f32 v150, v150, v61, v45
	v_max3_f32 v150, v150, v62, v46
	v_max3_f32 v150, v150, v63, v47
	ds_bpermute_b32 v151, v146, v150
	s_waitcnt lgkmcnt(0)
	v_max_f32_e32 v151, v151, v151
	v_max_f32_e32 v150, v150, v151
	v_mul_f32_e32 v150, 0x3e16c740, v150
	v_add_f32_e32 v151, 0x41000000, v138
	v_cmp_gt_f32_e32 vcc, v150, v151
	s_cbranch_vccz .LBB0_2452
	v_max_f32_e32 v150, v150, v150
	v_max_f32_e32 v151, v138, v138
	v_max_f32_e32 v150, v151, v150
	v_sub_f32_e32 v138, v138, v150
	v_exp_f32_e32 v138, v138
	s_nop 0
	v_pk_mul_f32 v[30:31], v[30:31], v[138:139] op_sel_hi:[1,0]
	v_pk_mul_f32 v[28:29], v[28:29], v[138:139] op_sel_hi:[1,0]
	v_pk_mul_f32 v[26:27], v[26:27], v[138:139] op_sel_hi:[1,0]
	v_pk_mul_f32 v[24:25], v[24:25], v[138:139] op_sel_hi:[1,0]
	v_pk_mul_f32 v[22:23], v[22:23], v[138:139] op_sel_hi:[1,0]
	v_pk_mul_f32 v[20:21], v[20:21], v[138:139] op_sel_hi:[1,0]
	v_pk_mul_f32 v[18:19], v[18:19], v[138:139] op_sel_hi:[1,0]
	v_pk_mul_f32 v[16:17], v[16:17], v[138:139] op_sel_hi:[1,0]
	v_pk_mul_f32 v[14:15], v[14:15], v[138:139] op_sel_hi:[1,0]
	v_pk_mul_f32 v[12:13], v[12:13], v[138:139] op_sel_hi:[1,0]
	v_pk_mul_f32 v[10:11], v[10:11], v[138:139] op_sel_hi:[1,0]
	v_pk_mul_f32 v[8:9], v[8:9], v[138:139] op_sel_hi:[1,0]
	v_pk_mul_f32 v[6:7], v[6:7], v[138:139] op_sel_hi:[1,0]
	v_pk_mul_f32 v[4:5], v[4:5], v[138:139] op_sel_hi:[1,0]
	v_pk_mul_f32 v[2:3], v[2:3], v[138:139] op_sel_hi:[1,0]
	v_pk_mul_f32 v[0:1], v[0:1], v[138:139] op_sel_hi:[1,0]
	v_mul_f32_e32 v149, v149, v138
	v_mov_b32_e32 v138, v150
	s_branch .LBB0_2452

.LBB0_3390:
	v_add_u32_e32 v16, s12, v130
	ds_read_b128 v[4:7], v16
	ds_read_b128 v[8:11], v16 offset:16
	ds_read_b128 v[12:15], v16 offset:32
	ds_read_b128 v[16:19], v16 offset:48
	v_ashrrev_i32_e32 v3, 31, v2
	v_lshlrev_b64 v[20:21], 13, v[2:3]
	s_waitcnt lgkmcnt(3)
	s_waitcnt lgkmcnt(2)
	s_waitcnt lgkmcnt(1)
	s_waitcnt lgkmcnt(0)
	v_max_f32_e32 v4, 0, v4
	v_max_f32_e32 v5, 0, v5
	v_max_f32_e32 v6, 0, v6
	v_max_f32_e32 v7, 0, v7
	v_max_f32_e32 v8, 0, v8
	v_max_f32_e32 v9, 0, v9
	v_max_f32_e32 v10, 0, v10
	v_max_f32_e32 v11, 0, v11
	s_addk_i32 s12, 0x4200
	v_max_f32_e32 v12, 0, v12
	v_max_f32_e32 v13, 0, v13
	v_max_f32_e32 v14, 0, v14
	v_max_f32_e32 v15, 0, v15
	v_max_f32_e32 v16, 0, v16
	v_max_f32_e32 v17, 0, v17
	v_max_f32_e32 v18, 0, v18
	v_max_f32_e32 v19, 0, v19
	v_pk_mul_f32 v[4:5], v[4:5], v[4:5]
	v_pk_mul_f32 v[6:7], v[6:7], v[6:7]
	v_pk_mul_f32 v[8:9], v[8:9], v[8:9]
	v_pk_mul_f32 v[10:11], v[10:11], v[10:11]
	v_add_u32_e32 v2, 32, v2
	s_cmp_lg_u32 s12, 0x10800
	v_lshl_add_u64 v[20:21], v[0:1], 0, v[20:21]
	v_pk_mul_f32 v[12:13], v[12:13], v[12:13]
	v_pk_mul_f32 v[14:15], v[14:15], v[14:15]
	v_pk_mul_f32 v[16:17], v[16:17], v[16:17]
	v_pk_mul_f32 v[18:19], v[18:19], v[18:19]
	v_cvt_pk_bf16_f32 v4, v4, v5
	v_cvt_pk_bf16_f32 v5, v6, v7
	v_cvt_pk_bf16_f32 v6, v8, v9
	v_cvt_pk_bf16_f32 v7, v10, v11
	v_cvt_pk_bf16_f32 v8, v12, v13
	v_cvt_pk_bf16_f32 v9, v14, v15
	v_cvt_pk_bf16_f32 v10, v16, v17
	v_cvt_pk_bf16_f32 v11, v18, v19
	global_store_dwordx4 v[20:21], v[4:7], off
	global_store_dwordx4 v[20:21], v[8:11], off offset:16
	s_cbranch_scc1 .LBB0_3390
	s_add_i32 s16, s16, s56
	v_add_u32_e32 v122, s14, v122
	v_add_u32_e32 v124, s14, v124
	v_add_u32_e32 v126, s14, v126
	s_cmpk_gt_i32 s16, 0xfff
	v_add_u32_e32 v64, s14, v64
	s_barrier
	s_cbranch_scc0 .LBB0_3387

.LBB0_3401:
	v_add_u32_e32 v16, s8, v128
	ds_read_b128 v[4:7], v16
	ds_read_b128 v[8:11], v16 offset:16
	ds_read_b128 v[12:15], v16 offset:32
	ds_read_b128 v[16:19], v16 offset:48
	v_ashrrev_i32_e32 v3, 31, v2
	v_lshlrev_b64 v[20:21], 13, v[2:3]
	s_waitcnt lgkmcnt(3)
	s_waitcnt lgkmcnt(2)
	s_waitcnt lgkmcnt(1)
	s_waitcnt lgkmcnt(0)
	v_max_f32_e32 v4, 0, v4
	v_max_f32_e32 v5, 0, v5
	v_max_f32_e32 v6, 0, v6
	v_max_f32_e32 v7, 0, v7
	v_max_f32_e32 v8, 0, v8
	v_max_f32_e32 v9, 0, v9
	v_max_f32_e32 v10, 0, v10
	v_max_f32_e32 v11, 0, v11
	s_addk_i32 s8, 0x4200
	v_max_f32_e32 v12, 0, v12
	v_max_f32_e32 v13, 0, v13
	v_max_f32_e32 v14, 0, v14
	v_max_f32_e32 v15, 0, v15
	v_max_f32_e32 v16, 0, v16
	v_max_f32_e32 v17, 0, v17
	v_max_f32_e32 v18, 0, v18
	v_max_f32_e32 v19, 0, v19
	v_pk_mul_f32 v[4:5], v[4:5], v[4:5]
	v_pk_mul_f32 v[6:7], v[6:7], v[6:7]
	v_pk_mul_f32 v[8:9], v[8:9], v[8:9]
	v_pk_mul_f32 v[10:11], v[10:11], v[10:11]
	v_add_u32_e32 v2, 32, v2
	s_cmp_lg_u32 s8, 0x10800
	v_lshl_add_u64 v[20:21], v[0:1], 0, v[20:21]
	v_pk_mul_f32 v[12:13], v[12:13], v[12:13]
	v_pk_mul_f32 v[14:15], v[14:15], v[14:15]
	v_pk_mul_f32 v[16:17], v[16:17], v[16:17]
	v_pk_mul_f32 v[18:19], v[18:19], v[18:19]
	v_cvt_pk_bf16_f32 v4, v4, v5
	v_cvt_pk_bf16_f32 v5, v6, v7
	v_cvt_pk_bf16_f32 v6, v8, v9
	v_cvt_pk_bf16_f32 v7, v10, v11
	v_cvt_pk_bf16_f32 v8, v12, v13
	v_cvt_pk_bf16_f32 v9, v14, v15
	v_cvt_pk_bf16_f32 v10, v16, v17
	v_cvt_pk_bf16_f32 v11, v18, v19
	global_store_dwordx4 v[20:21], v[4:7], off
	global_store_dwordx4 v[20:21], v[8:11], off offset:16
	s_cbranch_scc1 .LBB0_3401
	s_add_i32 s12, s12, s13
	s_cmpk_gt_i32 s12, 0x1ff
	s_barrier
	s_cbranch_scc0 .LBB0_3396
